# FOX back-edge rotation plus 196 bytes of unreachable padding after the FOX loop so that the later hot loops keep their 256-byte placement
# baseline (speedup 1.0000x reference)
.LBB0_272:
	v_exp_f32_e32 v112, v32
	v_exp_f32_e32 v125, v33
	v_exp_f32_e32 v144, v34
	v_exp_f32_e32 v145, v35
	v_exp_f32_e32 v36, v36
	v_exp_f32_e32 v37, v37
	v_exp_f32_e32 v38, v38
	v_exp_f32_e32 v39, v39
	v_cvt_pk_bf16_f32 v146, v112, v125
	v_cvt_pk_bf16_f32 v147, v144, v145
	v_cvt_pk_bf16_f32 v148, v36, v37
	v_cvt_pk_bf16_f32 v149, v38, v39
	v_exp_f32_e32 v40, v40
	v_exp_f32_e32 v41, v41
	v_exp_f32_e32 v42, v42
	v_exp_f32_e32 v43, v43
	v_exp_f32_e32 v44, v44
	v_exp_f32_e32 v45, v45
	v_exp_f32_e32 v46, v46
	v_exp_f32_e32 v47, v47
	v_mfma_f32_32x32x16_bf16 v[0:15], v[146:149], v[118:121], v[0:15]
	v_cvt_pk_bf16_f32 v150, v40, v41
	v_cvt_pk_bf16_f32 v151, v42, v43
	v_cvt_pk_bf16_f32 v152, v44, v45
	v_cvt_pk_bf16_f32 v153, v46, v47
	v_exp_f32_e32 v48, v48
	v_exp_f32_e32 v49, v49
	v_exp_f32_e32 v50, v50
	s_waitcnt lgkmcnt(6)
	v_mfma_f32_32x32x16_bf16 v[16:31], v[146:149], v[114:117], v[16:31]
	v_exp_f32_e32 v51, v51
	v_exp_f32_e32 v52, v52
	v_exp_f32_e32 v53, v53
	v_exp_f32_e32 v54, v54
	v_exp_f32_e32 v55, v55
	v_cvt_pk_bf16_f32 v192, v48, v49
	v_cvt_pk_bf16_f32 v193, v50, v51
	v_mfma_f32_32x32x16_bf16 v[0:15], v[150:153], v[108:111], v[0:15]
	v_cvt_pk_bf16_f32 v194, v52, v53
	v_cvt_pk_bf16_f32 v195, v54, v55
	v_exp_f32_e32 v56, v56
	v_exp_f32_e32 v57, v57
	v_exp_f32_e32 v58, v58
	v_exp_f32_e32 v59, v59
	v_exp_f32_e32 v60, v60
	s_waitcnt lgkmcnt(4)
	v_mfma_f32_32x32x16_bf16 v[16:31], v[150:153], v[104:107], v[16:31]
	v_exp_f32_e32 v61, v61
	v_exp_f32_e32 v62, v62
	v_exp_f32_e32 v63, v63
	v_cvt_pk_bf16_f32 v32, v56, v57
	v_cvt_pk_bf16_f32 v33, v58, v59
	v_cvt_pk_bf16_f32 v34, v60, v61
	v_cvt_pk_bf16_f32 v35, v62, v63
	v_mfma_f32_32x32x16_bf16 v[0:15], v[192:195], v[100:103], v[0:15]
	s_xor_b32 s0, s4, 1
	s_mulk_i32 s0, 0x5100
	s_addk_i32 s0, 0x100
	s_add_i32 s1, s0, s36
	s_and_b64 vcc, exec, s[38:39]
	s_waitcnt lgkmcnt(2)
	v_mfma_f32_32x32x16_bf16 v[16:31], v[192:195], v[96:99], v[16:31]
	v_mfma_f32_32x32x16_bf16 v[0:15], v[32:35], v[88:91], v[0:15]
	s_waitcnt lgkmcnt(0)
	v_mfma_f32_32x32x16_bf16 v[16:31], v[32:35], v[92:95], v[16:31]
	s_branch .LBB0_265
	s_nop 0
	s_nop 0
	s_nop 0
	s_nop 0
	s_nop 0
	s_nop 0
	s_nop 0
	s_nop 0
	s_nop 0
	s_nop 0
	s_nop 0
	s_nop 0
	s_nop 0
	s_nop 0
	s_nop 0
	s_nop 0
	s_nop 0
	s_nop 0
	s_nop 0
	s_nop 0
	s_nop 0
	s_nop 0
	s_nop 0
	s_nop 0
	s_nop 0
	s_nop 0
	s_nop 0
	s_nop 0
	s_nop 0
	s_nop 0
	s_nop 0
	s_nop 0
	s_nop 0
	s_nop 0
	s_nop 0
	s_nop 0
	s_nop 0
	s_nop 0
	s_nop 0
	s_nop 0
	s_nop 0
	s_nop 0
	s_nop 0
	s_nop 0
	s_nop 0
	s_nop 0
	s_nop 0
	s_nop 0
	s_nop 0
